# attention phase: static s_setprio 1 for waves 4-7
# baseline (speedup 1.0000x reference)
.LBB0_757:
	s_cmp_lt_i32 s60, 6
	s_cselect_b64 s[4:5], -1, 0
	s_and_b64 s[8:9], s[4:5], s[6:7]
	s_andn2_b64 vcc, exec, s[8:9]
	s_cbranch_vccnz .LBB0_857
	v_readfirstlane_b32 s98, v240
	s_nop 3
	s_lshr_b32 s98, s98, 8
	s_cmp_eq_u32 s98, 1
	s_cbranch_scc0 .Lattn_prio_skip
	s_setprio 1
.Lattn_prio_skip:
	v_readlane_b32 s44, v254, 29
	v_readlane_b32 s16, v254, 0
	s_waitcnt vmcnt(0)
	v_lshlrev_b32_e32 v0, 2, v241
	v_readlane_b32 s58, v254, 43
	v_readlane_b32 s59, v254, 44
	v_readlane_b32 s17, v254, 1
	v_mbcnt_lo_u32_b32 v2, -1, 0
	v_mbcnt_hi_u32_b32 v11, -1, v2
	v_and_b32_e32 v18, 64, v11
	v_xor_b32_e32 v20, 1, v11
	s_waitcnt lgkmcnt(0)
	global_load_dword v1, v0, s[58:59]
	global_load_dword v3, v0, s[16:17]
	v_add_u32_e32 v18, 64, v18
	v_cmp_lt_i32_e32 vcc, v20, v18
	v_xor_b32_e32 v21, 2, v11
	v_xor_b32_e32 v22, 4, v11
	v_cndmask_b32_e32 v20, v11, v20, vcc
	v_lshlrev_b32_e32 v20, 2, v20
	v_cmp_lt_i32_e32 vcc, v21, v18
	v_xor_b32_e32 v23, 8, v11
	v_xor_b32_e32 v24, 16, v11
	v_cndmask_b32_e32 v21, v11, v21, vcc
	v_lshlrev_b32_e32 v21, 2, v21
	v_cmp_lt_i32_e32 vcc, v22, v18
	v_xor_b32_e32 v25, 32, v11
	v_readlane_b32 s45, v254, 30
	v_cndmask_b32_e32 v22, v11, v22, vcc
	v_lshlrev_b32_e32 v22, 2, v22
	v_cmp_lt_i32_e32 vcc, v23, v18
	s_cmp_lt_i32 s34, 8
	s_cselect_b64 s[44:45], -1, 0
	v_cndmask_b32_e32 v23, v11, v23, vcc
	v_cmp_lt_i32_e32 vcc, v24, v18
	s_cmp_gt_i32 s34, 7
	s_cselect_b32 s3, 8, 1
	v_cndmask_b32_e32 v24, v11, v24, vcc
	v_cmp_lt_i32_e32 vcc, v25, v18
	v_lshlrev_b32_e32 v18, 2, v23
	v_cvt_f32_ubyte0_e32 v26, s3
	v_cndmask_b32_e32 v11, v11, v25, vcc
	v_lshlrev_b32_e32 v11, 2, v11
	s_movk_i32 s6, 0x80
	s_cselect_b32 s33, s6, 0x400
	s_add_u32 s68, s30, 0x12000400
	s_addc_u32 s69, s31, 0
	s_cmp_lg_u32 0, -1
	s_cselect_b32 s6, 0, 0
	s_add_i32 s73, 0, 0x14800
	s_addk_i32 s6, 0x6000
	s_add_u32 s90, s30, 0x5b00000
	s_addc_u32 s91, s31, 0
	s_add_u32 s92, s30, 0x8000
	s_addc_u32 s93, s31, 0
	s_sub_i32 s14, 0, s3
	s_abs_i32 s7, s2
	v_lshlrev_b32_e32 v6, 1, v240
	v_and_b32_e32 v13, 32, v6
	v_add_u32_e32 v19, 0, v13
	v_add_u32_e32 v13, s6, v13
	s_ashr_i32 s6, s2, 31
	v_and_b32_e32 v206, 31, v240
	v_lshrrev_b32_e32 v207, 5, v241
	v_mov_b32_e32 v4, 0x3f80
	v_lshlrev_b32_e32 v5, 3, v240
	v_lshlrev_b32_e32 v7, 4, v240
	v_lshrrev_b32_e32 v9, 3, v241
	v_cmp_gt_u32_e64 s[4:5], 32, v241
	v_readlane_b32 s52, v254, 37
	v_readlane_b32 s53, v254, 38
	v_mov_b32_e32 v98, 0x3f803f80
	v_cndmask_b32_e64 v101, 0, v4, s[4:5]
	v_and_b32_e32 v2, 24, v5
	v_and_b32_e32 v7, 0xc0, v7
	v_lshlrev_b32_e32 v10, 10, v207
	v_lshlrev_b32_e32 v12, 4, v206
	v_lshlrev_b32_e32 v8, 10, v206
	v_lshlrev_b32_e32 v15, 3, v206
	v_and_b32_e32 v4, 56, v5
	v_or_b32_e32 v5, 8, v9
	v_or_b32_e32 v16, 16, v9
	v_or_b32_e32 v17, 24, v9
	v_readlane_b32 s46, v254, 31
	v_readlane_b32 s47, v254, 32
	v_readlane_b32 s48, v254, 33
	v_readlane_b32 s49, v254, 34
	v_readlane_b32 s50, v254, 35
	v_readlane_b32 s51, v254, 36
	v_readlane_b32 s18, v254, 2
	s_mov_b32 s11, 0
	v_lshlrev_b32_e32 v0, 10, v241
	s_waitcnt vmcnt(1)
	v_and_b32_e32 v27, 0x7fffffff, v1
	s_waitcnt vmcnt(0)
	v_and_b32_e32 v28, 0x7fffffff, v3
	ds_bpermute_b32 v27, v20, v27
	ds_bpermute_b32 v20, v20, v28
	v_max_f32_e64 v1, |v1|, |v1|
	v_max_f32_e64 v3, |v3|, |v3|
	v_mov_b32_e32 v99, 0
	s_waitcnt lgkmcnt(1)
	v_max_f32_e32 v27, v27, v27
	s_waitcnt lgkmcnt(0)
	v_max_f32_e32 v20, v20, v20
	v_max_f32_e32 v1, v1, v27
	v_max_f32_e32 v3, v3, v20
	ds_bpermute_b32 v20, v21, v1
	ds_bpermute_b32 v21, v21, v3
	v_cndmask_b32_e64 v100, 0, v98, s[4:5]
	v_lshlrev_b32_e32 v6, 10, v9
	v_lshl_or_b32 v8, v207, 3, v8
	s_waitcnt lgkmcnt(1)
	v_max_f32_e32 v20, v20, v20
	s_waitcnt lgkmcnt(0)
	v_max_f32_e32 v21, v21, v21
	v_max_f32_e32 v1, v1, v20
	v_max_f32_e32 v3, v3, v21
	ds_bpermute_b32 v20, v22, v1
	ds_bpermute_b32 v21, v22, v3
	v_lshlrev_b32_e32 v22, 2, v24
	v_add3_u32 v209, 0, v10, v12
	v_lshlrev_b32_e32 v10, 10, v5
	s_waitcnt lgkmcnt(1)
	v_max_f32_e32 v20, v20, v20
	s_waitcnt lgkmcnt(0)
	v_max_f32_e32 v21, v21, v21
	v_max_f32_e32 v1, v1, v20
	v_max_f32_e32 v3, v3, v21
	ds_bpermute_b32 v20, v18, v1
	ds_bpermute_b32 v18, v18, v3
	v_rcp_iflag_f32_e32 v21, v26
	v_lshlrev_b32_e32 v12, 10, v16
	v_lshlrev_b32_e32 v14, 10, v17
	s_waitcnt lgkmcnt(1)
	v_max_f32_e32 v20, v20, v20
	s_waitcnt lgkmcnt(0)
	v_max_f32_e32 v18, v18, v18
	v_max_f32_e32 v1, v1, v20
	v_max_f32_e32 v3, v3, v18
	ds_bpermute_b32 v18, v22, v1
	ds_bpermute_b32 v20, v22, v3
	v_lshl_or_b32 v7, v207, 8, v7
	s_mov_b32 s52, 0xfffe0000
	s_mov_b32 s10, 0x3f803f80
	s_waitcnt lgkmcnt(1)
	v_max_f32_e32 v18, v18, v18
	s_waitcnt lgkmcnt(0)
	v_max_f32_e32 v20, v20, v20
	v_max_f32_e32 v1, v1, v18
	v_max_f32_e32 v3, v3, v20
	ds_bpermute_b32 v18, v11, v1
	ds_bpermute_b32 v11, v11, v3
	v_mov_b32_e32 v102, v99
	v_mov_b32_e32 v103, v99
	v_lshlrev_b32_e32 v208, 4, v207
	s_waitcnt lgkmcnt(1)
	v_max_f32_e32 v18, v18, v18
	s_waitcnt lgkmcnt(0)
	v_max_f32_e32 v11, v11, v11
	v_max_f32_e32 v3, v3, v11
	v_mul_f32_e32 v11, 0x4f7ffffe, v21
	v_cvt_u32_f32_e32 v11, v11
	v_max_f32_e32 v1, v1, v18
	v_mul_f32_e32 v1, 0x4138aa3b, v1
	v_mul_f32_e32 v1, v3, v1
	v_readfirstlane_b32 s15, v11
	s_mul_i32 s14, s14, s15
	s_mul_hi_u32 s14, s15, s14
	s_add_i32 s94, s15, s14
	s_mul_hi_u32 s14, s7, s94
	s_mul_i32 s14, s14, s3
	s_sub_i32 s7, s7, s14
	s_sub_i32 s14, s7, s3
	s_cmp_ge_u32 s7, s3
	s_cselect_b32 s7, s14, s7
	s_sub_i32 s14, s7, s3
	s_cmp_ge_u32 s7, s3
	s_cselect_b32 s7, s14, s7
	s_xor_b32 s7, s7, s6
	s_sub_i32 s95, s7, s6
	s_add_u32 s96, s30, 0xa000400
	v_readfirstlane_b32 s6, v1
	v_mov_b32_e32 v1, 0x3f8147ae
	s_addc_u32 s97, s31, 0
	v_mul_f32_e32 v1, s6, v1
	v_fmaak_f32 v219, 2.0, v1, 0x42200000
	s_add_u32 s14, s30, 0x5c00000
	v_add_u32_e32 v1, 0, v15
	v_add_u32_e32 v210, s73, v15
	v_lshrrev_b32_e32 v211, 2, v241
	v_add3_u32 v212, v13, v2, v7
	v_add3_u32 v213, v19, v2, v7
	v_mov_b32_e32 v104, v100
	v_mov_b32_e32 v107, v99
	v_lshlrev_b32_e32 v214, 9, v207
	v_lshlrev_b32_e32 v215, 7, v9
	v_lshlrev_b32_e32 v216, 7, v5
	v_lshlrev_b32_e32 v217, 7, v16
	v_lshlrev_b32_e32 v218, 7, v17
	s_addc_u32 s15, s31, 0
	v_add_u32_e32 v220, 0x14c00, v1
	v_add_u32_e32 v221, 0x14a00, v1
	s_add_i32 s16, 0, 0x20180
	v_lshlrev_b32_e32 v188, 1, v0
	v_lshlrev_b32_e32 v190, 1, v2
	s_mov_b64 s[46:47], 0x20000
	v_lshlrev_b32_e32 v222, 1, v8
	s_mov_b64 s[48:49], 0x40000
	s_mov_b64 s[50:51], 0x60000
	s_mov_b32 s53, -1
	s_mov_b32 s17, 0x42200000
	v_lshlrev_b32_e32 v192, 1, v4
	v_lshlrev_b32_e32 v194, 1, v6
	v_lshlrev_b32_e32 v196, 1, v10
	v_lshlrev_b32_e32 v198, 1, v12
	v_lshlrev_b32_e32 v200, 1, v14
	v_mov_b32_e32 v223, 0xff800000
	s_mov_b32 s18, s11
	v_readlane_b32 s54, v254, 39
	v_readlane_b32 s55, v254, 40
	v_readlane_b32 s56, v254, 41
	v_readlane_b32 s57, v254, 42
	v_readlane_b32 s19, v254, 3
	v_readlane_b32 s20, v254, 4
	v_readlane_b32 s21, v254, 5
	v_readlane_b32 s22, v254, 6
	v_readlane_b32 s23, v254, 7
	s_branch .LBB0_760

.LBB0_857:
	s_setprio 0
	s_cmp_gt_i32 s61, 6
	s_cselect_b64 s[6:7], -1, 0
	s_and_b64 s[4:5], s[8:9], s[6:7]
	s_andn2_b64 vcc, exec, s[4:5]
	s_cbranch_vccnz .LBB0_973
	s_waitcnt vmcnt(0)
	s_cmp_gt_u32 s28, 63
	s_mov_b64 s[4:5], -1
	s_waitcnt vmcnt(0) lgkmcnt(0)
	s_barrier
	s_cbranch_scc0 .LBB0_918
	s_andn2_b64 vcc, exec, s[62:63]
	s_cbranch_vccnz .LBB0_917
	s_mul_i32 s3, s2, 7
	v_readlane_b32 s4, v254, 48
	s_add_i32 s3, s3, s4
	s_addk_i32 s3, 0x1bff
	s_cmpk_gt_i32 s3, 0x407f
	s_cbranch_scc1 .LBB0_917
	s_cmpk_lt_i32 s3, 0x700
	s_movk_i32 s4, 0x4200
	s_cbranch_scc1 .LBB0_866
	s_cmpk_lt_u32 s3, 0x1200
	s_movk_i32 s4, 0x400
	s_cbranch_scc1 .LBB0_866
	s_cmpk_lt_u32 s3, 0x1780
	s_movk_i32 s4, 0x1f80
	s_cbranch_scc1 .LBB0_866
	s_cmpk_lt_u32 s3, 0x2280
	s_movk_i32 s4, 0xfe80
	s_cbranch_scc1 .LBB0_866
	s_cmpk_lt_u32 s3, 0x3b00
	s_movk_i32 s4, 0xf100
	s_cselect_b32 s4, s4, 0x180
	s_cmpk_gt_u32 s3, 0x2fff
	s_cselect_b32 s4, s4, 0x2100
	s_cmpk_gt_u32 s3, 0x27ff
	s_cselect_b32 s4, s4, 0x1480
